# v22 + first arriver of each XCD issues an early un-waited buffer_wbl2 sc1 at every grid barrier (leader flush unchanged)
# baseline (speedup 1.0000x reference)
; __device__ __forceinline__ unsigned xb_ld(unsigned* p)              { return __hip_atomic_load(p, __ATOMIC_RELAXED, __HIP_MEMORY_SCOPE_AGENT); }
; __device__ __forceinline__ unsigned xb_add(unsigned* p, unsigned v) { return __hip_atomic_fetch_add(p, v, __ATOMIC_RELAXED, __HIP_MEMORY_SCOPE_AGENT); }
; #define XB_SPIN(cond, bar) do { unsigned _sp = 0; while (cond) { __builtin_amdgcn_s_sleep(1); \
;     if ((++_sp & 255u) == 0u) { if (xb_ld(&(bar)[XB_TMO])) break; if (_sp > XB_SPIN_CAP) { atomicAdd(&(bar)[XB_TMO], 1u); break; } } } } while (0)
; __device__ __forceinline__ void xcd_barrier(const XcdBarrier& b, int tid) {
;     ...
;     if (tid == 0) {
;         unsigned* bar = b.bar; unsigned bx_ = b.x; asm volatile("" : "+s"(bar), "+s"(bx_));
;         __builtin_amdgcn_s_waitcnt(0);
;         unsigned nloc = b.st[0], nx = b.st[1];
;         if (nloc == 0u) { xcd_barrier_complete(bar, bx_, nloc, nx); b.st[0] = nloc; b.st[1] = nx; }
;         const unsigned old = xb_add(&bar[XB_XSUB(bx_)], 1u);
;         const unsigned gen = old / nloc;
;         if (old + 1u == (gen + 1u) * nloc) {
;             __builtin_amdgcn_fence(__ATOMIC_RELEASE, "agent");
;             asm volatile("s_waitcnt vmcnt(0)" ::: "memory");
;             const unsigned og = xb_add(&bar[XB_TOP], 1u);
;             const unsigned tg = og / nx;
;             if (og + 1u == (tg + 1u) * nx) xb_add(&bar[XB_TOPGEN], 1u);
;             else XB_SPIN(xb_ld(&bar[XB_TOPGEN]) == tg, bar);
;             __builtin_amdgcn_fence(__ATOMIC_ACQUIRE, "agent");
;             xb_add(&bar[XB_XGEN(bx_)], 1u);
;             asm volatile("s_waitcnt vmcnt(0)" ::: "memory");
;         } else {
;             XB_SPIN(xb_ld(&bar[XB_XGEN(bx_)]) == gen, bar);
.LBB0_90:
	s_lshl_b32 s24, s33, 6
	s_add_i32 s4, s24, 0x500
	s_mov_b32 s5, 0
	s_lshl_b64 s[0:1], s[4:5], 2
	s_add_u32 s0, s34, s0
	s_addc_u32 s1, s35, s1
	v_mov_b32_e32 v1, 1
	v_mov_b64_e32 v[4:5], s[0:1]
	flat_atomic_add v1, v[4:5], v1 sc0
	v_cvt_f32_u32_e32 v3, v2
	v_sub_u32_e32 v4, 0, v2
	v_rcp_iflag_f32_e32 v3, v3
	s_nop 0
	v_mul_f32_e32 v3, 0x4f7ffffe, v3
	v_cvt_u32_f32_e32 v3, v3
	v_mul_lo_u32 v4, v4, v3
	v_mul_hi_u32 v4, v3, v4
	v_add_u32_e32 v3, v3, v4
	s_waitcnt vmcnt(0) lgkmcnt(0)
	v_readfirstlane_b32 s8, v1
	v_readfirstlane_b32 s9, v2
	s_cmp_lt_u32 s9, 9
	s_cbranch_scc1 .Learlywb_1
	s_add_i32 s9, s9, -1
	s_and_b32 s8, s8, s9
	s_cmp_lg_u32 s8, 0
	s_cbranch_scc1 .Learlywb_1
	buffer_wbl2 sc1
.Learlywb_1:
	v_mul_hi_u32 v3, v1, v3
	v_mul_lo_u32 v5, v3, v2
	v_add_u32_e32 v4, 1, v1
	v_sub_u32_e32 v1, v1, v5
	v_add_u32_e32 v6, 1, v3
	v_cmp_ge_u32_e32 vcc, v1, v2
	v_sub_u32_e32 v5, v1, v2
	s_nop 0
	v_cndmask_b32_e32 v3, v3, v6, vcc
	v_cndmask_b32_e32 v1, v1, v5, vcc
	v_add_u32_e32 v5, 1, v3
	v_cmp_ge_u32_e32 vcc, v1, v2
	s_nop 1
	v_cndmask_b32_e32 v1, v3, v5, vcc
	v_mad_u64_u32 v[2:3], s[0:1], v2, v1, v[2:3]
	v_cmp_ne_u32_e32 vcc, v4, v2
	s_and_saveexec_b64 s[0:1], vcc
	s_xor_b64 s[0:1], exec, s[0:1]
	s_cbranch_execz .LBB0_103
	s_add_i32 s4, s24, 0x900
	s_lshl_b64 s[4:5], s[4:5], 2
	s_add_u32 s6, s34, s4
	s_addc_u32 s7, s35, s5
	v_mov_b64_e32 v[2:3], s[6:7]
	global_load_dword v0, v[2:3], off sc1
	s_waitcnt vmcnt(0) lgkmcnt(0)
	v_cmp_eq_u32_e32 vcc, v0, v1
	s_and_saveexec_b64 s[4:5], vcc
	s_cbranch_execz .LBB0_102
	s_mov_b32 s22, 1
	s_mov_b64 s[8:9], 0
	s_branch .LBB0_94

; __device__ __forceinline__ unsigned xb_ld(unsigned* p)              { return __hip_atomic_load(p, __ATOMIC_RELAXED, __HIP_MEMORY_SCOPE_AGENT); }
; __device__ __forceinline__ unsigned xb_add(unsigned* p, unsigned v) { return __hip_atomic_fetch_add(p, v, __ATOMIC_RELAXED, __HIP_MEMORY_SCOPE_AGENT); }
; #define XB_SPIN(cond, bar) do { unsigned _sp = 0; while (cond) { __builtin_amdgcn_s_sleep(1); \
;     if ((++_sp & 255u) == 0u) { if (xb_ld(&(bar)[XB_TMO])) break; if (_sp > XB_SPIN_CAP) { atomicAdd(&(bar)[XB_TMO], 1u); break; } } } } while (0)
; __device__ __forceinline__ void xcd_barrier(const XcdBarrier& b, int tid) {
;     ...
;     if (tid == 0) {
;         unsigned* bar = b.bar; unsigned bx_ = b.x; asm volatile("" : "+s"(bar), "+s"(bx_));
;         __builtin_amdgcn_s_waitcnt(0);
;         unsigned nloc = b.st[0], nx = b.st[1];
;         if (nloc == 0u) { xcd_barrier_complete(bar, bx_, nloc, nx); b.st[0] = nloc; b.st[1] = nx; }
;         const unsigned old = xb_add(&bar[XB_XSUB(bx_)], 1u);
;         const unsigned gen = old / nloc;
;         if (old + 1u == (gen + 1u) * nloc) {
;             __builtin_amdgcn_fence(__ATOMIC_RELEASE, "agent");
;             asm volatile("s_waitcnt vmcnt(0)" ::: "memory");
;             const unsigned og = xb_add(&bar[XB_TOP], 1u);
;             const unsigned tg = og / nx;
;             if (og + 1u == (tg + 1u) * nx) xb_add(&bar[XB_TOPGEN], 1u);
;             else XB_SPIN(xb_ld(&bar[XB_TOPGEN]) == tg, bar);
;             __builtin_amdgcn_fence(__ATOMIC_ACQUIRE, "agent");
;             xb_add(&bar[XB_XGEN(bx_)], 1u);
;             asm volatile("s_waitcnt vmcnt(0)" ::: "memory");
;         } else {
;             XB_SPIN(xb_ld(&bar[XB_XGEN(bx_)]) == gen, bar);
.LBB0_151:
	s_lshl_b32 s22, s33, 6
	s_add_i32 s4, s22, 0x500
	s_mov_b32 s5, 0
	s_lshl_b64 s[0:1], s[4:5], 2
	s_add_u32 s0, s34, s0
	s_addc_u32 s1, s35, s1
	v_mov_b32_e32 v1, 1
	v_mov_b64_e32 v[4:5], s[0:1]
	flat_atomic_add v1, v[4:5], v1 sc0
	v_cvt_f32_u32_e32 v3, v2
	v_sub_u32_e32 v4, 0, v2
	v_rcp_iflag_f32_e32 v3, v3
	s_nop 0
	v_mul_f32_e32 v3, 0x4f7ffffe, v3
	v_cvt_u32_f32_e32 v3, v3
	v_mul_lo_u32 v4, v4, v3
	v_mul_hi_u32 v4, v3, v4
	v_add_u32_e32 v3, v3, v4
	s_waitcnt vmcnt(0) lgkmcnt(0)
	v_readfirstlane_b32 s8, v1
	v_readfirstlane_b32 s9, v2
	s_cmp_lt_u32 s9, 9
	s_cbranch_scc1 .Learlywb_2
	s_add_i32 s9, s9, -1
	s_and_b32 s8, s8, s9
	s_cmp_lg_u32 s8, 0
	s_cbranch_scc1 .Learlywb_2
	buffer_wbl2 sc1
.Learlywb_2:
	v_mul_hi_u32 v3, v1, v3
	v_mul_lo_u32 v5, v3, v2
	v_add_u32_e32 v4, 1, v1
	v_sub_u32_e32 v1, v1, v5
	v_add_u32_e32 v6, 1, v3
	v_cmp_ge_u32_e32 vcc, v1, v2
	v_sub_u32_e32 v5, v1, v2
	s_nop 0
	v_cndmask_b32_e32 v3, v3, v6, vcc
	v_cndmask_b32_e32 v1, v1, v5, vcc
	v_add_u32_e32 v5, 1, v3
	v_cmp_ge_u32_e32 vcc, v1, v2
	s_nop 1
	v_cndmask_b32_e32 v1, v3, v5, vcc
	v_mad_u64_u32 v[2:3], s[0:1], v2, v1, v[2:3]
	v_cmp_ne_u32_e32 vcc, v4, v2
	s_and_saveexec_b64 s[0:1], vcc
	s_xor_b64 s[0:1], exec, s[0:1]
	s_cbranch_execz .LBB0_164
	s_add_i32 s4, s22, 0x900
	s_lshl_b64 s[4:5], s[4:5], 2
	s_add_u32 s6, s34, s4
	s_addc_u32 s7, s35, s5
	v_mov_b64_e32 v[2:3], s[6:7]
	global_load_dword v0, v[2:3], off sc1
	s_waitcnt vmcnt(0) lgkmcnt(0)
	v_cmp_eq_u32_e32 vcc, v0, v1
	s_and_saveexec_b64 s[4:5], vcc
	s_cbranch_execz .LBB0_163
	s_mov_b32 s23, 1
	s_mov_b64 s[8:9], 0
	s_branch .LBB0_155

; __device__ __forceinline__ unsigned xb_ld(unsigned* p)              { return __hip_atomic_load(p, __ATOMIC_RELAXED, __HIP_MEMORY_SCOPE_AGENT); }
; __device__ __forceinline__ unsigned xb_add(unsigned* p, unsigned v) { return __hip_atomic_fetch_add(p, v, __ATOMIC_RELAXED, __HIP_MEMORY_SCOPE_AGENT); }
; #define XB_SPIN(cond, bar) do { unsigned _sp = 0; while (cond) { __builtin_amdgcn_s_sleep(1); \
;     if ((++_sp & 255u) == 0u) { if (xb_ld(&(bar)[XB_TMO])) break; if (_sp > XB_SPIN_CAP) { atomicAdd(&(bar)[XB_TMO], 1u); break; } } } } while (0)
; __device__ __forceinline__ void xcd_barrier(const XcdBarrier& b, int tid) {
;     ...
;     if (tid == 0) {
;         unsigned* bar = b.bar; unsigned bx_ = b.x; asm volatile("" : "+s"(bar), "+s"(bx_));
;         __builtin_amdgcn_s_waitcnt(0);
;         unsigned nloc = b.st[0], nx = b.st[1];
;         if (nloc == 0u) { xcd_barrier_complete(bar, bx_, nloc, nx); b.st[0] = nloc; b.st[1] = nx; }
;         const unsigned old = xb_add(&bar[XB_XSUB(bx_)], 1u);
;         const unsigned gen = old / nloc;
;         if (old + 1u == (gen + 1u) * nloc) {
;             __builtin_amdgcn_fence(__ATOMIC_RELEASE, "agent");
;             asm volatile("s_waitcnt vmcnt(0)" ::: "memory");
;             const unsigned og = xb_add(&bar[XB_TOP], 1u);
;             const unsigned tg = og / nx;
;             if (og + 1u == (tg + 1u) * nx) xb_add(&bar[XB_TOPGEN], 1u);
;             else XB_SPIN(xb_ld(&bar[XB_TOPGEN]) == tg, bar);
;             __builtin_amdgcn_fence(__ATOMIC_ACQUIRE, "agent");
;             xb_add(&bar[XB_XGEN(bx_)], 1u);
;             asm volatile("s_waitcnt vmcnt(0)" ::: "memory");
;         } else {
;             XB_SPIN(xb_ld(&bar[XB_XGEN(bx_)]) == gen, bar);
.LBB0_213:
	s_lshl_b32 s24, s36, 6
	s_add_i32 s64, s24, 0x500
	s_lshl_b64 s[0:1], s[64:65], 2
	s_add_u32 s0, s34, s0
	s_addc_u32 s1, s35, s1
	v_mov_b64_e32 v[4:5], s[0:1]
	v_mov_b32_e32 v1, 1
	flat_atomic_add v3, v[4:5], v1 sc0
	v_cvt_f32_u32_e32 v1, v2
	v_sub_u32_e32 v4, 0, v2
	v_rcp_iflag_f32_e32 v1, v1
	s_nop 0
	v_mul_f32_e32 v1, 0x4f7ffffe, v1
	v_cvt_u32_f32_e32 v1, v1
	v_mul_lo_u32 v4, v4, v1
	v_mul_hi_u32 v4, v1, v4
	v_add_u32_e32 v1, v1, v4
	s_waitcnt vmcnt(0) lgkmcnt(0)
	v_readfirstlane_b32 s8, v3
	v_readfirstlane_b32 s9, v2
	s_cmp_lt_u32 s9, 9
	s_cbranch_scc1 .Learlywb_3
	s_add_i32 s9, s9, -1
	s_and_b32 s8, s8, s9
	s_cmp_lg_u32 s8, 0
	s_cbranch_scc1 .Learlywb_3
	buffer_wbl2 sc1
.Learlywb_3:
	v_mul_hi_u32 v1, v3, v1
	v_mul_lo_u32 v4, v1, v2
	v_sub_u32_e32 v4, v3, v4
	v_cmp_ge_u32_e32 vcc, v4, v2
	v_add_u32_e32 v5, 1, v1
	s_nop 0
	v_cndmask_b32_e32 v1, v1, v5, vcc
	v_sub_u32_e32 v5, v4, v2
	v_cndmask_b32_e32 v4, v4, v5, vcc
	v_cmp_ge_u32_e32 vcc, v4, v2
	v_add_u32_e32 v4, 1, v1
	s_nop 0
	v_cndmask_b32_e32 v1, v1, v4, vcc
	v_add_u32_e32 v4, 1, v3
	v_mad_u64_u32 v[2:3], s[0:1], v2, v1, v[2:3]
	v_cmp_ne_u32_e32 vcc, v4, v2
	s_and_saveexec_b64 s[0:1], vcc
	s_xor_b64 s[0:1], exec, s[0:1]
	s_cbranch_execz .LBB0_226
	s_add_i32 s64, s24, 0x900
	s_lshl_b64 s[4:5], s[64:65], 2
	s_add_u32 s6, s34, s4
	s_addc_u32 s7, s35, s5
	v_mov_b64_e32 v[2:3], s[6:7]
	global_load_dword v0, v[2:3], off sc1
	s_waitcnt vmcnt(0) lgkmcnt(0)
	v_cmp_eq_u32_e32 vcc, v0, v1
	s_and_saveexec_b64 s[4:5], vcc
	s_cbranch_execz .LBB0_225
	s_mov_b32 s22, 1
	s_mov_b64 s[8:9], 0
	s_branch .LBB0_217

; __device__ __forceinline__ unsigned xb_ld(unsigned* p)              { return __hip_atomic_load(p, __ATOMIC_RELAXED, __HIP_MEMORY_SCOPE_AGENT); }
; __device__ __forceinline__ unsigned xb_add(unsigned* p, unsigned v) { return __hip_atomic_fetch_add(p, v, __ATOMIC_RELAXED, __HIP_MEMORY_SCOPE_AGENT); }
; #define XB_SPIN(cond, bar) do { unsigned _sp = 0; while (cond) { __builtin_amdgcn_s_sleep(1); \
;     if ((++_sp & 255u) == 0u) { if (xb_ld(&(bar)[XB_TMO])) break; if (_sp > XB_SPIN_CAP) { atomicAdd(&(bar)[XB_TMO], 1u); break; } } } } while (0)
; __device__ __forceinline__ void xcd_barrier(const XcdBarrier& b, int tid) {
;     ...
;     if (tid == 0) {
;         unsigned* bar = b.bar; unsigned bx_ = b.x; asm volatile("" : "+s"(bar), "+s"(bx_));
;         __builtin_amdgcn_s_waitcnt(0);
;         unsigned nloc = b.st[0], nx = b.st[1];
;         if (nloc == 0u) { xcd_barrier_complete(bar, bx_, nloc, nx); b.st[0] = nloc; b.st[1] = nx; }
;         const unsigned old = xb_add(&bar[XB_XSUB(bx_)], 1u);
;         const unsigned gen = old / nloc;
;         if (old + 1u == (gen + 1u) * nloc) {
;             __builtin_amdgcn_fence(__ATOMIC_RELEASE, "agent");
;             asm volatile("s_waitcnt vmcnt(0)" ::: "memory");
;             const unsigned og = xb_add(&bar[XB_TOP], 1u);
;             const unsigned tg = og / nx;
;             if (og + 1u == (tg + 1u) * nx) xb_add(&bar[XB_TOPGEN], 1u);
;             else XB_SPIN(xb_ld(&bar[XB_TOPGEN]) == tg, bar);
;             __builtin_amdgcn_fence(__ATOMIC_ACQUIRE, "agent");
;             xb_add(&bar[XB_XGEN(bx_)], 1u);
;             asm volatile("s_waitcnt vmcnt(0)" ::: "memory");
;         } else {
;             XB_SPIN(xb_ld(&bar[XB_XGEN(bx_)]) == gen, bar);
.LBB0_772:
	s_lshl_b32 s0, s0, 6
	s_add_i32 s64, s0, 0x500
	s_lshl_b64 s[4:5], s[64:65], 2
	s_add_u32 s4, s36, s4
	s_addc_u32 s5, s37, s5
	v_mov_b64_e32 v[4:5], s[4:5]
	v_mov_b32_e32 v1, 1
	flat_atomic_add v3, v[4:5], v1 sc0
	v_cvt_f32_u32_e32 v1, v2
	v_sub_u32_e32 v4, 0, v2
	v_rcp_iflag_f32_e32 v1, v1
	s_nop 0
	v_mul_f32_e32 v1, 0x4f7ffffe, v1
	v_cvt_u32_f32_e32 v1, v1
	v_mul_lo_u32 v4, v4, v1
	v_mul_hi_u32 v4, v1, v4
	v_add_u32_e32 v1, v1, v4
	s_waitcnt vmcnt(0) lgkmcnt(0)
	v_readfirstlane_b32 s8, v3
	v_readfirstlane_b32 s9, v2
	s_cmp_lt_u32 s9, 9
	s_cbranch_scc1 .Learlywb_5
	s_add_i32 s9, s9, -1
	s_and_b32 s8, s8, s9
	s_cmp_lg_u32 s8, 0
	s_cbranch_scc1 .Learlywb_5
	buffer_wbl2 sc1
.Learlywb_5:
	v_mul_hi_u32 v1, v3, v1
	v_mul_lo_u32 v4, v1, v2
	v_sub_u32_e32 v4, v3, v4
	v_cmp_ge_u32_e32 vcc, v4, v2
	v_add_u32_e32 v5, 1, v1
	s_nop 0
	v_cndmask_b32_e32 v1, v1, v5, vcc
	v_sub_u32_e32 v5, v4, v2
	v_cndmask_b32_e32 v4, v4, v5, vcc
	v_cmp_ge_u32_e32 vcc, v4, v2
	v_add_u32_e32 v4, 1, v1
	s_nop 0
	v_cndmask_b32_e32 v1, v1, v4, vcc
	v_add_u32_e32 v4, 1, v3
	v_mad_u64_u32 v[2:3], s[4:5], v2, v1, v[2:3]
	v_cmp_ne_u32_e32 vcc, v4, v2
	s_and_saveexec_b64 s[4:5], vcc
	s_xor_b64 s[4:5], exec, s[4:5]
	s_cbranch_execz .LBB0_785
	s_add_i32 s64, s0, 0x900
	s_lshl_b64 s[6:7], s[64:65], 2
	s_add_u32 s8, s36, s6
	s_addc_u32 s9, s37, s7
	v_mov_b64_e32 v[2:3], s[8:9]
	global_load_dword v0, v[2:3], off sc1
	s_waitcnt vmcnt(0) lgkmcnt(0)
	v_cmp_eq_u32_e32 vcc, v0, v1
	s_and_saveexec_b64 s[6:7], vcc
	s_cbranch_execz .LBB0_784
	s_mov_b32 s1, 1
	s_mov_b64 s[10:11], 0
	s_branch .LBB0_776

; __device__ __forceinline__ unsigned xb_ld(unsigned* p)              { return __hip_atomic_load(p, __ATOMIC_RELAXED, __HIP_MEMORY_SCOPE_AGENT); }
; __device__ __forceinline__ unsigned xb_add(unsigned* p, unsigned v) { return __hip_atomic_fetch_add(p, v, __ATOMIC_RELAXED, __HIP_MEMORY_SCOPE_AGENT); }
; #define XB_SPIN(cond, bar) do { unsigned _sp = 0; while (cond) { __builtin_amdgcn_s_sleep(1); \
;     if ((++_sp & 255u) == 0u) { if (xb_ld(&(bar)[XB_TMO])) break; if (_sp > XB_SPIN_CAP) { atomicAdd(&(bar)[XB_TMO], 1u); break; } } } } while (0)
; __device__ __forceinline__ void xcd_barrier(const XcdBarrier& b, int tid) {
;     ...
;     if (tid == 0) {
;         unsigned* bar = b.bar; unsigned bx_ = b.x; asm volatile("" : "+s"(bar), "+s"(bx_));
;         __builtin_amdgcn_s_waitcnt(0);
;         unsigned nloc = b.st[0], nx = b.st[1];
;         if (nloc == 0u) { xcd_barrier_complete(bar, bx_, nloc, nx); b.st[0] = nloc; b.st[1] = nx; }
;         const unsigned old = xb_add(&bar[XB_XSUB(bx_)], 1u);
;         const unsigned gen = old / nloc;
;         if (old + 1u == (gen + 1u) * nloc) {
;             __builtin_amdgcn_fence(__ATOMIC_RELEASE, "agent");
;             asm volatile("s_waitcnt vmcnt(0)" ::: "memory");
;             const unsigned og = xb_add(&bar[XB_TOP], 1u);
;             const unsigned tg = og / nx;
;             if (og + 1u == (tg + 1u) * nx) xb_add(&bar[XB_TOPGEN], 1u);
;             else XB_SPIN(xb_ld(&bar[XB_TOPGEN]) == tg, bar);
;             __builtin_amdgcn_fence(__ATOMIC_ACQUIRE, "agent");
;             xb_add(&bar[XB_XGEN(bx_)], 1u);
;             asm volatile("s_waitcnt vmcnt(0)" ::: "memory");
;         } else {
;             XB_SPIN(xb_ld(&bar[XB_XGEN(bx_)]) == gen, bar);
.LBB0_934:
	s_lshl_b32 s26, s36, 6
	s_add_i32 s64, s26, 0x500
	s_lshl_b64 s[4:5], s[64:65], 2
	s_add_u32 s4, s2, s4
	s_addc_u32 s5, s3, s5
	v_mov_b64_e32 v[4:5], s[4:5]
	v_mov_b32_e32 v1, 1
	flat_atomic_add v3, v[4:5], v1 sc0
	v_cvt_f32_u32_e32 v1, v2
	v_sub_u32_e32 v4, 0, v2
	v_rcp_iflag_f32_e32 v1, v1
	s_nop 0
	v_mul_f32_e32 v1, 0x4f7ffffe, v1
	v_cvt_u32_f32_e32 v1, v1
	v_mul_lo_u32 v4, v4, v1
	v_mul_hi_u32 v4, v1, v4
	v_add_u32_e32 v1, v1, v4
	s_waitcnt vmcnt(0) lgkmcnt(0)
	v_readfirstlane_b32 s8, v3
	v_readfirstlane_b32 s9, v2
	s_cmp_lt_u32 s9, 9
	s_cbranch_scc1 .Learlywb_6
	s_add_i32 s9, s9, -1
	s_and_b32 s8, s8, s9
	s_cmp_lg_u32 s8, 0
	s_cbranch_scc1 .Learlywb_6
	buffer_wbl2 sc1
.Learlywb_6:
	v_mul_hi_u32 v1, v3, v1
	v_mul_lo_u32 v4, v1, v2
	v_sub_u32_e32 v4, v3, v4
	v_cmp_ge_u32_e32 vcc, v4, v2
	v_add_u32_e32 v5, 1, v1
	s_nop 0
	v_cndmask_b32_e32 v1, v1, v5, vcc
	v_sub_u32_e32 v5, v4, v2
	v_cndmask_b32_e32 v4, v4, v5, vcc
	v_cmp_ge_u32_e32 vcc, v4, v2
	v_add_u32_e32 v4, 1, v1
	s_nop 0
	v_cndmask_b32_e32 v1, v1, v4, vcc
	v_add_u32_e32 v4, 1, v3
	v_mad_u64_u32 v[2:3], s[4:5], v2, v1, v[2:3]
	v_cmp_ne_u32_e32 vcc, v4, v2
	s_and_saveexec_b64 s[4:5], vcc
	s_xor_b64 s[4:5], exec, s[4:5]
	s_cbranch_execz .LBB0_947
	s_add_i32 s64, s26, 0x900
	s_lshl_b64 s[6:7], s[64:65], 2
	s_add_u32 s8, s2, s6
	s_addc_u32 s9, s3, s7
	v_mov_b64_e32 v[2:3], s[8:9]
	global_load_dword v0, v[2:3], off sc1
	s_waitcnt vmcnt(0) lgkmcnt(0)
	v_cmp_eq_u32_e32 vcc, v0, v1
	s_and_saveexec_b64 s[6:7], vcc
	s_cbranch_execz .LBB0_946
	s_mov_b32 s24, 1
	s_mov_b64 s[10:11], 0
	s_branch .LBB0_938

; __device__ __forceinline__ unsigned xb_ld(unsigned* p)              { return __hip_atomic_load(p, __ATOMIC_RELAXED, __HIP_MEMORY_SCOPE_AGENT); }
; __device__ __forceinline__ unsigned xb_add(unsigned* p, unsigned v) { return __hip_atomic_fetch_add(p, v, __ATOMIC_RELAXED, __HIP_MEMORY_SCOPE_AGENT); }
; #define XB_SPIN(cond, bar) do { unsigned _sp = 0; while (cond) { __builtin_amdgcn_s_sleep(1); \
;     if ((++_sp & 255u) == 0u) { if (xb_ld(&(bar)[XB_TMO])) break; if (_sp > XB_SPIN_CAP) { atomicAdd(&(bar)[XB_TMO], 1u); break; } } } } while (0)
; __device__ __forceinline__ void xcd_barrier(const XcdBarrier& b, int tid) {
;     ...
;     if (tid == 0) {
;         unsigned* bar = b.bar; unsigned bx_ = b.x; asm volatile("" : "+s"(bar), "+s"(bx_));
;         __builtin_amdgcn_s_waitcnt(0);
;         unsigned nloc = b.st[0], nx = b.st[1];
;         if (nloc == 0u) { xcd_barrier_complete(bar, bx_, nloc, nx); b.st[0] = nloc; b.st[1] = nx; }
;         const unsigned old = xb_add(&bar[XB_XSUB(bx_)], 1u);
;         const unsigned gen = old / nloc;
;         if (old + 1u == (gen + 1u) * nloc) {
;             __builtin_amdgcn_fence(__ATOMIC_RELEASE, "agent");
;             asm volatile("s_waitcnt vmcnt(0)" ::: "memory");
;             const unsigned og = xb_add(&bar[XB_TOP], 1u);
;             const unsigned tg = og / nx;
;             if (og + 1u == (tg + 1u) * nx) xb_add(&bar[XB_TOPGEN], 1u);
;             else XB_SPIN(xb_ld(&bar[XB_TOPGEN]) == tg, bar);
;             __builtin_amdgcn_fence(__ATOMIC_ACQUIRE, "agent");
;             xb_add(&bar[XB_XGEN(bx_)], 1u);
;             asm volatile("s_waitcnt vmcnt(0)" ::: "memory");
;         } else {
;             XB_SPIN(xb_ld(&bar[XB_XGEN(bx_)]) == gen, bar);
.LBB0_1031:
	s_lshl_b32 s28, s50, 6
	s_add_i32 s64, s28, 0x500
	s_lshl_b64 s[6:7], s[64:65], 2
	s_add_u32 s6, s2, s6
	s_addc_u32 s7, s3, s7
	v_mov_b64_e32 v[4:5], s[6:7]
	v_mov_b32_e32 v1, 1
	flat_atomic_add v3, v[4:5], v1 sc0
	v_cvt_f32_u32_e32 v1, v2
	v_sub_u32_e32 v4, 0, v2
	v_rcp_iflag_f32_e32 v1, v1
	s_nop 0
	v_mul_f32_e32 v1, 0x4f7ffffe, v1
	v_cvt_u32_f32_e32 v1, v1
	v_mul_lo_u32 v4, v4, v1
	v_mul_hi_u32 v4, v1, v4
	v_add_u32_e32 v1, v1, v4
	s_waitcnt vmcnt(0) lgkmcnt(0)
	v_readfirstlane_b32 s8, v3
	v_readfirstlane_b32 s9, v2
	s_cmp_lt_u32 s9, 9
	s_cbranch_scc1 .Learlywb_7
	s_add_i32 s9, s9, -1
	s_and_b32 s8, s8, s9
	s_cmp_lg_u32 s8, 0
	s_cbranch_scc1 .Learlywb_7
	buffer_wbl2 sc1
.Learlywb_7:
	v_mul_hi_u32 v1, v3, v1
	v_mul_lo_u32 v4, v1, v2
	v_sub_u32_e32 v4, v3, v4
	v_cmp_ge_u32_e32 vcc, v4, v2
	v_add_u32_e32 v5, 1, v1
	s_nop 0
	v_cndmask_b32_e32 v1, v1, v5, vcc
	v_sub_u32_e32 v5, v4, v2
	v_cndmask_b32_e32 v4, v4, v5, vcc
	v_cmp_ge_u32_e32 vcc, v4, v2
	v_add_u32_e32 v4, 1, v1
	s_nop 0
	v_cndmask_b32_e32 v1, v1, v4, vcc
	v_add_u32_e32 v4, 1, v3
	v_mad_u64_u32 v[2:3], s[6:7], v2, v1, v[2:3]
	v_cmp_ne_u32_e32 vcc, v4, v2
	s_and_saveexec_b64 s[6:7], vcc
	s_xor_b64 s[6:7], exec, s[6:7]
	s_cbranch_execz .LBB0_1044
	s_add_i32 s64, s28, 0x900
	s_lshl_b64 s[8:9], s[64:65], 2
	s_add_u32 s10, s2, s8
	s_addc_u32 s11, s3, s9
	v_mov_b64_e32 v[2:3], s[10:11]
	global_load_dword v0, v[2:3], off sc1
	s_waitcnt vmcnt(0) lgkmcnt(0)
	v_cmp_eq_u32_e32 vcc, v0, v1
	s_and_saveexec_b64 s[8:9], vcc
	s_cbranch_execz .LBB0_1043
	s_mov_b32 s26, 1
	s_mov_b64 s[12:13], 0
	s_branch .LBB0_1035

; __device__ __forceinline__ unsigned xb_ld(unsigned* p)              { return __hip_atomic_load(p, __ATOMIC_RELAXED, __HIP_MEMORY_SCOPE_AGENT); }
; __device__ __forceinline__ unsigned xb_add(unsigned* p, unsigned v) { return __hip_atomic_fetch_add(p, v, __ATOMIC_RELAXED, __HIP_MEMORY_SCOPE_AGENT); }
; #define XB_SPIN(cond, bar) do { unsigned _sp = 0; while (cond) { __builtin_amdgcn_s_sleep(1); \
;     if ((++_sp & 255u) == 0u) { if (xb_ld(&(bar)[XB_TMO])) break; if (_sp > XB_SPIN_CAP) { atomicAdd(&(bar)[XB_TMO], 1u); break; } } } } while (0)
; __device__ __forceinline__ void xcd_barrier(const XcdBarrier& b, int tid) {
;     ...
;     if (tid == 0) {
;         unsigned* bar = b.bar; unsigned bx_ = b.x; asm volatile("" : "+s"(bar), "+s"(bx_));
;         __builtin_amdgcn_s_waitcnt(0);
;         unsigned nloc = b.st[0], nx = b.st[1];
;         if (nloc == 0u) { xcd_barrier_complete(bar, bx_, nloc, nx); b.st[0] = nloc; b.st[1] = nx; }
;         const unsigned old = xb_add(&bar[XB_XSUB(bx_)], 1u);
;         const unsigned gen = old / nloc;
;         if (old + 1u == (gen + 1u) * nloc) {
;             __builtin_amdgcn_fence(__ATOMIC_RELEASE, "agent");
;             asm volatile("s_waitcnt vmcnt(0)" ::: "memory");
;             const unsigned og = xb_add(&bar[XB_TOP], 1u);
;             const unsigned tg = og / nx;
;             if (og + 1u == (tg + 1u) * nx) xb_add(&bar[XB_TOPGEN], 1u);
;             else XB_SPIN(xb_ld(&bar[XB_TOPGEN]) == tg, bar);
;             __builtin_amdgcn_fence(__ATOMIC_ACQUIRE, "agent");
;             xb_add(&bar[XB_XGEN(bx_)], 1u);
;             asm volatile("s_waitcnt vmcnt(0)" ::: "memory");
;         } else {
;             XB_SPIN(xb_ld(&bar[XB_XGEN(bx_)]) == gen, bar);
.LBB0_1101:
	s_lshl_b32 s26, s50, 6
	s_add_i32 s64, s26, 0x500
	s_lshl_b64 s[6:7], s[64:65], 2
	s_add_u32 s6, s58, s6
	s_addc_u32 s7, s59, s7
	v_mov_b64_e32 v[4:5], s[6:7]
	v_mov_b32_e32 v1, 1
	flat_atomic_add v3, v[4:5], v1 sc0
	v_cvt_f32_u32_e32 v1, v2
	v_sub_u32_e32 v4, 0, v2
	v_rcp_iflag_f32_e32 v1, v1
	s_nop 0
	v_mul_f32_e32 v1, 0x4f7ffffe, v1
	v_cvt_u32_f32_e32 v1, v1
	v_mul_lo_u32 v4, v4, v1
	v_mul_hi_u32 v4, v1, v4
	v_add_u32_e32 v1, v1, v4
	s_waitcnt vmcnt(0) lgkmcnt(0)
	v_readfirstlane_b32 s8, v3
	v_readfirstlane_b32 s9, v2
	s_cmp_lt_u32 s9, 9
	s_cbranch_scc1 .Learlywb_8
	s_add_i32 s9, s9, -1
	s_and_b32 s8, s8, s9
	s_cmp_lg_u32 s8, 0
	s_cbranch_scc1 .Learlywb_8
	buffer_wbl2 sc1
.Learlywb_8:
	v_mul_hi_u32 v1, v3, v1
	v_mul_lo_u32 v4, v1, v2
	v_sub_u32_e32 v4, v3, v4
	v_cmp_ge_u32_e32 vcc, v4, v2
	v_add_u32_e32 v5, 1, v1
	s_nop 0
	v_cndmask_b32_e32 v1, v1, v5, vcc
	v_sub_u32_e32 v5, v4, v2
	v_cndmask_b32_e32 v4, v4, v5, vcc
	v_cmp_ge_u32_e32 vcc, v4, v2
	v_add_u32_e32 v4, 1, v1
	s_nop 0
	v_cndmask_b32_e32 v1, v1, v4, vcc
	v_add_u32_e32 v4, 1, v3
	v_mad_u64_u32 v[2:3], s[6:7], v2, v1, v[2:3]
	v_cmp_ne_u32_e32 vcc, v4, v2
	s_and_saveexec_b64 s[6:7], vcc
	s_xor_b64 s[6:7], exec, s[6:7]
	s_cbranch_execz .LBB0_1114
	s_add_i32 s64, s26, 0x900
	s_lshl_b64 s[8:9], s[64:65], 2
	s_add_u32 s10, s58, s8
	s_addc_u32 s11, s59, s9
	v_mov_b64_e32 v[2:3], s[10:11]
	global_load_dword v0, v[2:3], off sc1
	s_waitcnt vmcnt(0) lgkmcnt(0)
	v_cmp_eq_u32_e32 vcc, v0, v1
	s_and_saveexec_b64 s[8:9], vcc
	s_cbranch_execz .LBB0_1113
	s_mov_b32 s27, 1
	s_mov_b64 s[12:13], 0
	s_branch .LBB0_1105

; __device__ __forceinline__ unsigned xb_ld(unsigned* p)              { return __hip_atomic_load(p, __ATOMIC_RELAXED, __HIP_MEMORY_SCOPE_AGENT); }
; __device__ __forceinline__ unsigned xb_add(unsigned* p, unsigned v) { return __hip_atomic_fetch_add(p, v, __ATOMIC_RELAXED, __HIP_MEMORY_SCOPE_AGENT); }
; #define XB_SPIN(cond, bar) do { unsigned _sp = 0; while (cond) { __builtin_amdgcn_s_sleep(1); \
;     if ((++_sp & 255u) == 0u) { if (xb_ld(&(bar)[XB_TMO])) break; if (_sp > XB_SPIN_CAP) { atomicAdd(&(bar)[XB_TMO], 1u); break; } } } } while (0)
; __device__ __forceinline__ void xcd_barrier(const XcdBarrier& b, int tid) {
;     ...
;     if (tid == 0) {
;         unsigned* bar = b.bar; unsigned bx_ = b.x; asm volatile("" : "+s"(bar), "+s"(bx_));
;         __builtin_amdgcn_s_waitcnt(0);
;         unsigned nloc = b.st[0], nx = b.st[1];
;         if (nloc == 0u) { xcd_barrier_complete(bar, bx_, nloc, nx); b.st[0] = nloc; b.st[1] = nx; }
;         const unsigned old = xb_add(&bar[XB_XSUB(bx_)], 1u);
;         const unsigned gen = old / nloc;
;         if (old + 1u == (gen + 1u) * nloc) {
;             __builtin_amdgcn_fence(__ATOMIC_RELEASE, "agent");
;             asm volatile("s_waitcnt vmcnt(0)" ::: "memory");
;             const unsigned og = xb_add(&bar[XB_TOP], 1u);
;             const unsigned tg = og / nx;
;             if (og + 1u == (tg + 1u) * nx) xb_add(&bar[XB_TOPGEN], 1u);
;             else XB_SPIN(xb_ld(&bar[XB_TOPGEN]) == tg, bar);
;             __builtin_amdgcn_fence(__ATOMIC_ACQUIRE, "agent");
;             xb_add(&bar[XB_XGEN(bx_)], 1u);
;             asm volatile("s_waitcnt vmcnt(0)" ::: "memory");
;         } else {
;             XB_SPIN(xb_ld(&bar[XB_XGEN(bx_)]) == gen, bar);
.LBB0_1151:
	s_lshl_b32 s28, s50, 6
	s_add_i32 s64, s28, 0x500
	s_lshl_b64 s[6:7], s[64:65], 2
	s_add_u32 s6, s58, s6
	s_addc_u32 s7, s59, s7
	v_mov_b64_e32 v[4:5], s[6:7]
	v_mov_b32_e32 v1, 1
	flat_atomic_add v3, v[4:5], v1 sc0
	v_cvt_f32_u32_e32 v1, v2
	v_sub_u32_e32 v4, 0, v2
	v_rcp_iflag_f32_e32 v1, v1
	s_nop 0
	v_mul_f32_e32 v1, 0x4f7ffffe, v1
	v_cvt_u32_f32_e32 v1, v1
	v_mul_lo_u32 v4, v4, v1
	v_mul_hi_u32 v4, v1, v4
	v_add_u32_e32 v1, v1, v4
	s_waitcnt vmcnt(0) lgkmcnt(0)
	v_readfirstlane_b32 s8, v3
	v_readfirstlane_b32 s9, v2
	s_cmp_lt_u32 s9, 9
	s_cbranch_scc1 .Learlywb_9
	s_add_i32 s9, s9, -1
	s_and_b32 s8, s8, s9
	s_cmp_lg_u32 s8, 0
	s_cbranch_scc1 .Learlywb_9
	buffer_wbl2 sc1
.Learlywb_9:
	v_mul_hi_u32 v1, v3, v1
	v_mul_lo_u32 v4, v1, v2
	v_sub_u32_e32 v4, v3, v4
	v_cmp_ge_u32_e32 vcc, v4, v2
	v_add_u32_e32 v5, 1, v1
	s_nop 0
	v_cndmask_b32_e32 v1, v1, v5, vcc
	v_sub_u32_e32 v5, v4, v2
	v_cndmask_b32_e32 v4, v4, v5, vcc
	v_cmp_ge_u32_e32 vcc, v4, v2
	v_add_u32_e32 v4, 1, v1
	s_nop 0
	v_cndmask_b32_e32 v1, v1, v4, vcc
	v_add_u32_e32 v4, 1, v3
	v_mad_u64_u32 v[2:3], s[6:7], v2, v1, v[2:3]
	v_cmp_ne_u32_e32 vcc, v4, v2
	s_and_saveexec_b64 s[6:7], vcc
	s_xor_b64 s[6:7], exec, s[6:7]
	s_cbranch_execz .LBB0_1164
	s_add_i32 s64, s28, 0x900
	s_lshl_b64 s[8:9], s[64:65], 2
	s_add_u32 s10, s58, s8
	s_addc_u32 s11, s59, s9
	v_mov_b64_e32 v[2:3], s[10:11]
	global_load_dword v0, v[2:3], off sc1
	s_waitcnt vmcnt(0) lgkmcnt(0)
	v_cmp_eq_u32_e32 vcc, v0, v1
	s_and_saveexec_b64 s[8:9], vcc
	s_cbranch_execz .LBB0_1163
	s_mov_b32 s26, 1
	s_mov_b64 s[12:13], 0
	s_branch .LBB0_1155

; __device__ __forceinline__ unsigned xb_ld(unsigned* p)              { return __hip_atomic_load(p, __ATOMIC_RELAXED, __HIP_MEMORY_SCOPE_AGENT); }
; __device__ __forceinline__ unsigned xb_add(unsigned* p, unsigned v) { return __hip_atomic_fetch_add(p, v, __ATOMIC_RELAXED, __HIP_MEMORY_SCOPE_AGENT); }
; #define XB_SPIN(cond, bar) do { unsigned _sp = 0; while (cond) { __builtin_amdgcn_s_sleep(1); \
;     if ((++_sp & 255u) == 0u) { if (xb_ld(&(bar)[XB_TMO])) break; if (_sp > XB_SPIN_CAP) { atomicAdd(&(bar)[XB_TMO], 1u); break; } } } } while (0)
; __device__ __forceinline__ void xcd_barrier(const XcdBarrier& b, int tid) {
;     ...
;     if (tid == 0) {
;         unsigned* bar = b.bar; unsigned bx_ = b.x; asm volatile("" : "+s"(bar), "+s"(bx_));
;         __builtin_amdgcn_s_waitcnt(0);
;         unsigned nloc = b.st[0], nx = b.st[1];
;         if (nloc == 0u) { xcd_barrier_complete(bar, bx_, nloc, nx); b.st[0] = nloc; b.st[1] = nx; }
;         const unsigned old = xb_add(&bar[XB_XSUB(bx_)], 1u);
;         const unsigned gen = old / nloc;
;         if (old + 1u == (gen + 1u) * nloc) {
;             __builtin_amdgcn_fence(__ATOMIC_RELEASE, "agent");
;             asm volatile("s_waitcnt vmcnt(0)" ::: "memory");
;             const unsigned og = xb_add(&bar[XB_TOP], 1u);
;             const unsigned tg = og / nx;
;             if (og + 1u == (tg + 1u) * nx) xb_add(&bar[XB_TOPGEN], 1u);
;             else XB_SPIN(xb_ld(&bar[XB_TOPGEN]) == tg, bar);
;             __builtin_amdgcn_fence(__ATOMIC_ACQUIRE, "agent");
;             xb_add(&bar[XB_XGEN(bx_)], 1u);
;             asm volatile("s_waitcnt vmcnt(0)" ::: "memory");
;         } else {
;             XB_SPIN(xb_ld(&bar[XB_XGEN(bx_)]) == gen, bar);
.LBB0_1293:
	s_lshl_b32 s22, s36, 6
	s_add_i32 s64, s22, 0x500
	s_lshl_b64 s[0:1], s[64:65], 2
	s_add_u32 s0, s34, s0
	s_addc_u32 s1, s35, s1
	v_mov_b64_e32 v[4:5], s[0:1]
	v_mov_b32_e32 v1, 1
	flat_atomic_add v3, v[4:5], v1 sc0
	v_cvt_f32_u32_e32 v1, v2
	v_sub_u32_e32 v4, 0, v2
	v_rcp_iflag_f32_e32 v1, v1
	s_nop 0
	v_mul_f32_e32 v1, 0x4f7ffffe, v1
	v_cvt_u32_f32_e32 v1, v1
	v_mul_lo_u32 v4, v4, v1
	v_mul_hi_u32 v4, v1, v4
	v_add_u32_e32 v1, v1, v4
	s_waitcnt vmcnt(0) lgkmcnt(0)
	v_readfirstlane_b32 s8, v3
	v_readfirstlane_b32 s9, v2
	s_cmp_lt_u32 s9, 9
	s_cbranch_scc1 .Learlywb_11
	s_add_i32 s9, s9, -1
	s_and_b32 s8, s8, s9
	s_cmp_lg_u32 s8, 0
	s_cbranch_scc1 .Learlywb_11
	buffer_wbl2 sc1
.Learlywb_11:
	v_mul_hi_u32 v1, v3, v1
	v_mul_lo_u32 v4, v1, v2
	v_sub_u32_e32 v4, v3, v4
	v_cmp_ge_u32_e32 vcc, v4, v2
	v_add_u32_e32 v5, 1, v1
	s_nop 0
	v_cndmask_b32_e32 v1, v1, v5, vcc
	v_sub_u32_e32 v5, v4, v2
	v_cndmask_b32_e32 v4, v4, v5, vcc
	v_cmp_ge_u32_e32 vcc, v4, v2
	v_add_u32_e32 v4, 1, v1
	s_nop 0
	v_cndmask_b32_e32 v1, v1, v4, vcc
	v_add_u32_e32 v4, 1, v3
	v_mad_u64_u32 v[2:3], s[0:1], v2, v1, v[2:3]
	v_cmp_ne_u32_e32 vcc, v4, v2
	s_and_saveexec_b64 s[0:1], vcc
	s_xor_b64 s[0:1], exec, s[0:1]
	s_cbranch_execz .LBB0_1306
	s_add_i32 s64, s22, 0x900
	s_lshl_b64 s[4:5], s[64:65], 2
	s_add_u32 s6, s34, s4
	s_addc_u32 s7, s35, s5
	v_mov_b64_e32 v[2:3], s[6:7]
	global_load_dword v0, v[2:3], off sc1
	s_waitcnt vmcnt(0) lgkmcnt(0)
	v_cmp_eq_u32_e32 vcc, v0, v1
	s_and_saveexec_b64 s[4:5], vcc
	s_cbranch_execz .LBB0_1305
	s_mov_b32 s23, 1
	s_mov_b64 s[8:9], 0
	s_branch .LBB0_1297
